# phase I and J epilogue stores made write-through (sc1) so the grid barrier's L2 write-back has little left to flush
# speedup vs baseline: 1.0024x; 1.0024x over previous
.LBB0_2428:
	v_mul_f32_e32 v147, 0xbfb8aa3b, v126
	v_exp_f32_e32 v147, v147
	s_lshl_b32 s13, s22, 8
	v_mbcnt_lo_u32_b32 v140, -1, 0
	v_mbcnt_hi_u32_b32 v140, -1, v140
	s_add_i32 s13, s13, s45
	v_add_f32_e32 v147, 1.0, v147
	v_rcp_f32_e32 v150, v147
	v_mul_f32_e32 v147, 0xbfb8aa3b, v127
	v_exp_f32_e32 v147, v147
	v_and_or_b32 v146, v140, 15, s13
	s_lshl_b32 s13, s20, 7
	v_ashrrev_i32_e32 v140, 1, v140
	v_add_f32_e32 v147, 1.0, v147
	v_rcp_f32_e32 v151, v147
	s_or_b32 s13, s13, s47
	v_and_b32_e32 v140, -8, v140
	v_add_u32_e32 v142, s13, v140
	v_pk_mul_f32 v[126:127], v[126:127], v[150:151]
	v_ashrrev_i32_e32 v143, 31, v142
	v_pk_mul_f32 v[122:123], v[122:123], v[126:127]
	v_mov_b64_e32 v[140:141], s[8:9]
	v_cvt_pk_bf16_f32 v122, v122, v123
	v_mul_f32_e32 v123, 0xbfb8aa3b, v128
	v_exp_f32_e32 v123, v123
	v_mad_i64_i32 v[148:149], s[20:21], v146, s59, v[140:141]
	v_lshlrev_b64 v[142:143], 1, v[142:143]
	v_add_f32_e32 v123, 1.0, v123
	v_rcp_f32_e32 v126, v123
	v_mul_f32_e32 v123, 0xbfb8aa3b, v129
	v_exp_f32_e32 v123, v123
	v_lshl_add_u64 v[148:149], v[148:149], 0, v[142:143]
	s_andn2_b64 vcc, exec, s[6:7]
	v_add_f32_e32 v123, 1.0, v123
	v_rcp_f32_e32 v127, v123
	s_nop 0
	v_pk_mul_f32 v[126:127], v[128:129], v[126:127]
	s_nop 0
	v_pk_mul_f32 v[124:125], v[124:125], v[126:127]
	s_nop 0
	v_cvt_pk_bf16_f32 v123, v124, v125
	v_mul_f32_e32 v124, 0xbfb8aa3b, v118
	v_mul_f32_e32 v125, 0xbfb8aa3b, v119
	v_exp_f32_e32 v124, v124
	v_exp_f32_e32 v125, v125
	v_add_f32_e32 v124, 1.0, v124
	v_add_f32_e32 v125, 1.0, v125
	v_rcp_f32_e32 v124, v124
	v_rcp_f32_e32 v125, v125
	s_nop 0
	v_pk_mul_f32 v[118:119], v[118:119], v[124:125]
	s_nop 0
	v_pk_mul_f32 v[114:115], v[114:115], v[118:119]
	s_nop 0
	v_cvt_pk_bf16_f32 v124, v114, v115
	v_mul_f32_e32 v114, 0xbfb8aa3b, v120
	v_mul_f32_e32 v115, 0xbfb8aa3b, v121
	v_exp_f32_e32 v114, v114
	v_exp_f32_e32 v115, v115
	v_add_f32_e32 v114, 1.0, v114
	v_add_f32_e32 v115, 1.0, v115
	v_rcp_f32_e32 v114, v114
	v_rcp_f32_e32 v115, v115
	s_nop 0
	v_pk_mul_f32 v[114:115], v[120:121], v[114:115]
	s_nop 0
	v_pk_mul_f32 v[114:115], v[116:117], v[114:115]
	v_mul_f32_e32 v116, 0xbfb8aa3b, v110
	v_mul_f32_e32 v117, 0xbfb8aa3b, v111
	v_exp_f32_e32 v116, v116
	v_exp_f32_e32 v117, v117
	v_cvt_pk_bf16_f32 v125, v114, v115
	v_or_b32_e32 v114, 16, v146
	v_add_f32_e32 v116, 1.0, v116
	v_add_f32_e32 v117, 1.0, v117
	v_rcp_f32_e32 v116, v116
	v_rcp_f32_e32 v117, v117
	v_mad_i64_i32 v[114:115], s[20:21], v114, s59, v[140:141]
	v_lshl_add_u64 v[114:115], v[114:115], 0, v[142:143]
	v_pk_mul_f32 v[110:111], v[110:111], v[116:117]
	global_store_dwordx4 v[148:149], v[122:125], off sc1
	v_pk_mul_f32 v[106:107], v[106:107], v[110:111]
	s_nop 0
	v_cvt_pk_bf16_f32 v106, v106, v107
	v_mul_f32_e32 v107, 0xbfb8aa3b, v112
	v_exp_f32_e32 v107, v107
	s_nop 0
	v_add_f32_e32 v107, 1.0, v107
	v_rcp_f32_e32 v110, v107
	v_mul_f32_e32 v107, 0xbfb8aa3b, v113
	v_exp_f32_e32 v107, v107
	s_nop 0
	v_add_f32_e32 v107, 1.0, v107
	v_rcp_f32_e32 v111, v107
	s_nop 0
	v_pk_mul_f32 v[110:111], v[112:113], v[110:111]
	s_nop 0
	v_pk_mul_f32 v[108:109], v[108:109], v[110:111]
	s_nop 0
	v_cvt_pk_bf16_f32 v107, v108, v109
	v_mul_f32_e32 v108, 0xbfb8aa3b, v102
	v_mul_f32_e32 v109, 0xbfb8aa3b, v103
	v_exp_f32_e32 v108, v108
	v_exp_f32_e32 v109, v109
	v_add_f32_e32 v108, 1.0, v108
	v_add_f32_e32 v109, 1.0, v109
	v_rcp_f32_e32 v108, v108
	v_rcp_f32_e32 v109, v109
	s_nop 0
	v_pk_mul_f32 v[102:103], v[102:103], v[108:109]
	s_nop 0
	v_pk_mul_f32 v[98:99], v[98:99], v[102:103]
	s_nop 0
	v_cvt_pk_bf16_f32 v108, v98, v99
	v_mul_f32_e32 v98, 0xbfb8aa3b, v104
	v_mul_f32_e32 v99, 0xbfb8aa3b, v105
	v_exp_f32_e32 v98, v98
	v_exp_f32_e32 v99, v99
	v_add_f32_e32 v98, 1.0, v98
	v_add_f32_e32 v99, 1.0, v99
	v_rcp_f32_e32 v98, v98
	v_rcp_f32_e32 v99, v99
	s_nop 0
	v_pk_mul_f32 v[98:99], v[104:105], v[98:99]
	s_nop 0
	v_pk_mul_f32 v[98:99], v[100:101], v[98:99]
	v_mul_f32_e32 v100, 0xbfb8aa3b, v94
	v_mul_f32_e32 v101, 0xbfb8aa3b, v95
	v_exp_f32_e32 v100, v100
	v_exp_f32_e32 v101, v101
	v_cvt_pk_bf16_f32 v109, v98, v99
	v_or_b32_e32 v98, 32, v146
	v_add_f32_e32 v100, 1.0, v100
	v_add_f32_e32 v101, 1.0, v101
	v_rcp_f32_e32 v100, v100
	v_rcp_f32_e32 v101, v101
	v_mad_i64_i32 v[98:99], s[20:21], v98, s59, v[140:141]
	v_lshl_add_u64 v[98:99], v[98:99], 0, v[142:143]
	v_pk_mul_f32 v[94:95], v[94:95], v[100:101]
	global_store_dwordx4 v[114:115], v[106:109], off sc1
	v_pk_mul_f32 v[90:91], v[90:91], v[94:95]
	s_nop 0
	v_cvt_pk_bf16_f32 v90, v90, v91
	v_mul_f32_e32 v91, 0xbfb8aa3b, v96
	v_exp_f32_e32 v91, v91
	s_nop 0
	v_add_f32_e32 v91, 1.0, v91
	v_rcp_f32_e32 v94, v91
	v_mul_f32_e32 v91, 0xbfb8aa3b, v97
	v_exp_f32_e32 v91, v91
	s_nop 0
	v_add_f32_e32 v91, 1.0, v91
	v_rcp_f32_e32 v95, v91
	s_nop 0
	v_pk_mul_f32 v[94:95], v[96:97], v[94:95]
	s_nop 0
	v_pk_mul_f32 v[92:93], v[92:93], v[94:95]
	s_nop 0
	v_cvt_pk_bf16_f32 v91, v92, v93
	v_mul_f32_e32 v92, 0xbfb8aa3b, v86
	v_mul_f32_e32 v93, 0xbfb8aa3b, v87
	v_exp_f32_e32 v92, v92
	v_exp_f32_e32 v93, v93
	v_add_f32_e32 v92, 1.0, v92
	v_add_f32_e32 v93, 1.0, v93
	v_rcp_f32_e32 v92, v92
	v_rcp_f32_e32 v93, v93
	s_nop 0
	v_pk_mul_f32 v[86:87], v[86:87], v[92:93]
	s_nop 0
	v_pk_mul_f32 v[82:83], v[82:83], v[86:87]
	s_nop 0
	v_cvt_pk_bf16_f32 v92, v82, v83
	v_mul_f32_e32 v82, 0xbfb8aa3b, v88
	v_mul_f32_e32 v83, 0xbfb8aa3b, v89
	v_exp_f32_e32 v82, v82
	v_exp_f32_e32 v83, v83
	v_add_f32_e32 v82, 1.0, v82
	v_add_f32_e32 v83, 1.0, v83
	v_rcp_f32_e32 v82, v82
	v_rcp_f32_e32 v83, v83
	s_nop 0
	v_pk_mul_f32 v[82:83], v[88:89], v[82:83]
	s_nop 0
	v_pk_mul_f32 v[82:83], v[84:85], v[82:83]
	v_mul_f32_e32 v84, 0xbfb8aa3b, v78
	v_mul_f32_e32 v85, 0xbfb8aa3b, v79
	v_exp_f32_e32 v84, v84
	v_exp_f32_e32 v85, v85
	v_cvt_pk_bf16_f32 v93, v82, v83
	v_or_b32_e32 v82, 48, v146
	v_add_f32_e32 v84, 1.0, v84
	v_add_f32_e32 v85, 1.0, v85
	v_rcp_f32_e32 v84, v84
	v_rcp_f32_e32 v85, v85
	v_mad_i64_i32 v[82:83], s[20:21], v82, s59, v[140:141]
	v_lshl_add_u64 v[82:83], v[82:83], 0, v[142:143]
	v_pk_mul_f32 v[78:79], v[78:79], v[84:85]
	global_store_dwordx4 v[98:99], v[90:93], off sc1
	v_pk_mul_f32 v[74:75], v[74:75], v[78:79]
	s_nop 0
	v_cvt_pk_bf16_f32 v74, v74, v75
	v_mul_f32_e32 v75, 0xbfb8aa3b, v80
	v_exp_f32_e32 v75, v75
	s_nop 0
	v_add_f32_e32 v75, 1.0, v75
	v_rcp_f32_e32 v78, v75
	v_mul_f32_e32 v75, 0xbfb8aa3b, v81
	v_exp_f32_e32 v75, v75
	s_nop 0
	v_add_f32_e32 v75, 1.0, v75
	v_rcp_f32_e32 v79, v75
	s_nop 0
	v_pk_mul_f32 v[78:79], v[80:81], v[78:79]
	s_nop 0
	v_pk_mul_f32 v[76:77], v[76:77], v[78:79]
	s_nop 0
	v_cvt_pk_bf16_f32 v75, v76, v77
	v_mul_f32_e32 v76, 0xbfb8aa3b, v70
	v_mul_f32_e32 v77, 0xbfb8aa3b, v71
	v_exp_f32_e32 v76, v76
	v_exp_f32_e32 v77, v77
	v_add_f32_e32 v76, 1.0, v76
	v_add_f32_e32 v77, 1.0, v77
	v_rcp_f32_e32 v76, v76
	v_rcp_f32_e32 v77, v77
	s_nop 0
	v_pk_mul_f32 v[70:71], v[70:71], v[76:77]
	s_nop 0
	v_pk_mul_f32 v[66:67], v[66:67], v[70:71]
	s_nop 0
	v_cvt_pk_bf16_f32 v76, v66, v67
	v_mul_f32_e32 v66, 0xbfb8aa3b, v72
	v_mul_f32_e32 v67, 0xbfb8aa3b, v73
	v_exp_f32_e32 v66, v66
	v_exp_f32_e32 v67, v67
	v_add_f32_e32 v66, 1.0, v66
	v_add_f32_e32 v67, 1.0, v67
	v_rcp_f32_e32 v66, v66
	v_rcp_f32_e32 v67, v67
	s_nop 0
	v_pk_mul_f32 v[66:67], v[72:73], v[66:67]
	s_nop 0
	v_pk_mul_f32 v[66:67], v[68:69], v[66:67]
	v_mul_f32_e32 v68, 0xbfb8aa3b, v60
	v_mul_f32_e32 v69, 0xbfb8aa3b, v61
	v_exp_f32_e32 v68, v68
	v_exp_f32_e32 v69, v69
	v_cvt_pk_bf16_f32 v77, v66, v67
	v_add_u32_e32 v66, 0x80, v146
	v_add_f32_e32 v68, 1.0, v68
	v_add_f32_e32 v69, 1.0, v69
	v_rcp_f32_e32 v68, v68
	v_rcp_f32_e32 v69, v69
	v_mad_i64_i32 v[66:67], s[20:21], v66, s59, v[140:141]
	v_lshl_add_u64 v[66:67], v[66:67], 0, v[142:143]
	v_pk_mul_f32 v[60:61], v[60:61], v[68:69]
	global_store_dwordx4 v[82:83], v[74:77], off sc1
	v_pk_mul_f32 v[56:57], v[56:57], v[60:61]
	s_nop 0
	v_cvt_pk_bf16_f32 v56, v56, v57
	v_mul_f32_e32 v57, 0xbfb8aa3b, v62
	v_exp_f32_e32 v57, v57
	s_nop 0
	v_add_f32_e32 v57, 1.0, v57
	v_rcp_f32_e32 v60, v57
	v_mul_f32_e32 v57, 0xbfb8aa3b, v63
	v_exp_f32_e32 v57, v57
	s_nop 0
	v_add_f32_e32 v57, 1.0, v57
	v_rcp_f32_e32 v61, v57
	s_nop 0
	v_pk_mul_f32 v[60:61], v[62:63], v[60:61]
	s_nop 0
	v_pk_mul_f32 v[58:59], v[58:59], v[60:61]
	s_nop 0
	v_cvt_pk_bf16_f32 v57, v58, v59
	v_mul_f32_e32 v58, 0xbfb8aa3b, v52
	v_mul_f32_e32 v59, 0xbfb8aa3b, v53
	v_exp_f32_e32 v58, v58
	v_exp_f32_e32 v59, v59
	v_add_f32_e32 v58, 1.0, v58
	v_add_f32_e32 v59, 1.0, v59
	v_rcp_f32_e32 v58, v58
	v_rcp_f32_e32 v59, v59
	s_nop 0
	v_pk_mul_f32 v[52:53], v[52:53], v[58:59]
	s_nop 0
	v_pk_mul_f32 v[48:49], v[48:49], v[52:53]
	s_nop 0
	v_cvt_pk_bf16_f32 v58, v48, v49
	v_mul_f32_e32 v48, 0xbfb8aa3b, v54
	v_mul_f32_e32 v49, 0xbfb8aa3b, v55
	v_exp_f32_e32 v48, v48
	v_exp_f32_e32 v49, v49
	v_add_f32_e32 v48, 1.0, v48
	v_add_f32_e32 v49, 1.0, v49
	v_rcp_f32_e32 v48, v48
	v_rcp_f32_e32 v49, v49
	s_nop 0
	v_pk_mul_f32 v[48:49], v[54:55], v[48:49]
	s_nop 0
	v_pk_mul_f32 v[48:49], v[50:51], v[48:49]
	v_mul_f32_e32 v50, 0xbfb8aa3b, v44
	v_mul_f32_e32 v51, 0xbfb8aa3b, v45
	v_exp_f32_e32 v50, v50
	v_exp_f32_e32 v51, v51
	v_cvt_pk_bf16_f32 v59, v48, v49
	v_add_u32_e32 v48, 0x90, v146
	v_add_f32_e32 v50, 1.0, v50
	v_add_f32_e32 v51, 1.0, v51
	v_rcp_f32_e32 v50, v50
	v_rcp_f32_e32 v51, v51
	v_mad_i64_i32 v[48:49], s[20:21], v48, s59, v[140:141]
	v_lshl_add_u64 v[48:49], v[48:49], 0, v[142:143]
	v_pk_mul_f32 v[44:45], v[44:45], v[50:51]
	global_store_dwordx4 v[66:67], v[56:59], off sc1
	v_pk_mul_f32 v[40:41], v[40:41], v[44:45]
	s_nop 0
	v_cvt_pk_bf16_f32 v40, v40, v41
	v_mul_f32_e32 v41, 0xbfb8aa3b, v46
	v_exp_f32_e32 v41, v41
	s_nop 0
	v_add_f32_e32 v41, 1.0, v41
	v_rcp_f32_e32 v44, v41
	v_mul_f32_e32 v41, 0xbfb8aa3b, v47
	v_exp_f32_e32 v41, v41
	s_nop 0
	v_add_f32_e32 v41, 1.0, v41
	v_rcp_f32_e32 v45, v41
	s_nop 0
	v_pk_mul_f32 v[44:45], v[46:47], v[44:45]
	s_nop 0
	v_pk_mul_f32 v[42:43], v[42:43], v[44:45]
	s_nop 0
	v_cvt_pk_bf16_f32 v41, v42, v43
	v_mul_f32_e32 v42, 0xbfb8aa3b, v36
	v_mul_f32_e32 v43, 0xbfb8aa3b, v37
	v_exp_f32_e32 v42, v42
	v_exp_f32_e32 v43, v43
	v_add_f32_e32 v42, 1.0, v42
	v_add_f32_e32 v43, 1.0, v43
	v_rcp_f32_e32 v42, v42
	v_rcp_f32_e32 v43, v43
	s_nop 0
	v_pk_mul_f32 v[36:37], v[36:37], v[42:43]
	s_nop 0
	v_pk_mul_f32 v[32:33], v[32:33], v[36:37]
	s_nop 0
	v_cvt_pk_bf16_f32 v42, v32, v33
	v_mul_f32_e32 v32, 0xbfb8aa3b, v38
	v_mul_f32_e32 v33, 0xbfb8aa3b, v39
	v_exp_f32_e32 v32, v32
	v_exp_f32_e32 v33, v33
	v_add_f32_e32 v32, 1.0, v32
	v_add_f32_e32 v33, 1.0, v33
	v_rcp_f32_e32 v32, v32
	v_rcp_f32_e32 v33, v33
	s_nop 0
	v_pk_mul_f32 v[32:33], v[38:39], v[32:33]
	s_nop 0
	v_pk_mul_f32 v[32:33], v[34:35], v[32:33]
	v_mul_f32_e32 v34, 0xbfb8aa3b, v28
	v_mul_f32_e32 v35, 0xbfb8aa3b, v29
	v_exp_f32_e32 v34, v34
	v_exp_f32_e32 v35, v35
	v_cvt_pk_bf16_f32 v43, v32, v33
	v_add_u32_e32 v32, 0xa0, v146
	v_add_f32_e32 v34, 1.0, v34
	v_add_f32_e32 v35, 1.0, v35
	v_rcp_f32_e32 v34, v34
	v_rcp_f32_e32 v35, v35
	v_mad_i64_i32 v[32:33], s[20:21], v32, s59, v[140:141]
	v_lshl_add_u64 v[32:33], v[32:33], 0, v[142:143]
	v_pk_mul_f32 v[28:29], v[28:29], v[34:35]
	global_store_dwordx4 v[48:49], v[40:43], off sc1
	v_pk_mul_f32 v[24:25], v[24:25], v[28:29]
	s_nop 0
	v_cvt_pk_bf16_f32 v24, v24, v25
	v_mul_f32_e32 v25, 0xbfb8aa3b, v30
	v_exp_f32_e32 v25, v25
	s_nop 0
	v_add_f32_e32 v25, 1.0, v25
	v_rcp_f32_e32 v28, v25
	v_mul_f32_e32 v25, 0xbfb8aa3b, v31
	v_exp_f32_e32 v25, v25
	s_nop 0
	v_add_f32_e32 v25, 1.0, v25
	v_rcp_f32_e32 v29, v25
	s_nop 0
	v_pk_mul_f32 v[28:29], v[30:31], v[28:29]
	s_nop 0
	v_pk_mul_f32 v[26:27], v[26:27], v[28:29]
	s_nop 0
	v_cvt_pk_bf16_f32 v25, v26, v27
	v_mul_f32_e32 v26, 0xbfb8aa3b, v20
	v_mul_f32_e32 v27, 0xbfb8aa3b, v21
	v_exp_f32_e32 v26, v26
	v_exp_f32_e32 v27, v27
	v_add_f32_e32 v26, 1.0, v26
	v_add_f32_e32 v27, 1.0, v27
	v_rcp_f32_e32 v26, v26
	v_rcp_f32_e32 v27, v27
	s_nop 0
	v_pk_mul_f32 v[20:21], v[20:21], v[26:27]
	s_nop 0
	v_pk_mul_f32 v[16:17], v[16:17], v[20:21]
	s_nop 0
	v_cvt_pk_bf16_f32 v26, v16, v17
	v_mul_f32_e32 v16, 0xbfb8aa3b, v22
	v_mul_f32_e32 v17, 0xbfb8aa3b, v23
	v_exp_f32_e32 v16, v16
	v_exp_f32_e32 v17, v17
	v_add_f32_e32 v16, 1.0, v16
	v_add_f32_e32 v17, 1.0, v17
	v_rcp_f32_e32 v16, v16
	v_rcp_f32_e32 v17, v17
	s_nop 0
	v_pk_mul_f32 v[16:17], v[22:23], v[16:17]
	s_nop 0
	v_pk_mul_f32 v[16:17], v[18:19], v[16:17]
	v_mul_f32_e32 v18, 0xbfb8aa3b, v12
	v_mul_f32_e32 v19, 0xbfb8aa3b, v13
	v_exp_f32_e32 v18, v18
	v_exp_f32_e32 v19, v19
	v_cvt_pk_bf16_f32 v27, v16, v17
	v_add_u32_e32 v16, 0xb0, v146
	v_add_f32_e32 v18, 1.0, v18
	v_add_f32_e32 v19, 1.0, v19
	v_rcp_f32_e32 v18, v18
	v_rcp_f32_e32 v19, v19
	v_mad_i64_i32 v[16:17], s[20:21], v16, s59, v[140:141]
	v_lshl_add_u64 v[16:17], v[16:17], 0, v[142:143]
	v_pk_mul_f32 v[12:13], v[12:13], v[18:19]
	s_mov_b64 s[20:21], -1
	v_pk_mul_f32 v[8:9], v[8:9], v[12:13]
	global_store_dwordx4 v[32:33], v[24:27], off sc1
	v_cvt_pk_bf16_f32 v8, v8, v9
	v_mul_f32_e32 v9, 0xbfb8aa3b, v14
	v_exp_f32_e32 v9, v9
	s_nop 0
	v_add_f32_e32 v9, 1.0, v9
	v_rcp_f32_e32 v12, v9
	v_mul_f32_e32 v9, 0xbfb8aa3b, v15
	v_exp_f32_e32 v9, v9
	s_nop 0
	v_add_f32_e32 v9, 1.0, v9
	v_rcp_f32_e32 v13, v9
	s_nop 0
	v_pk_mul_f32 v[12:13], v[14:15], v[12:13]
	s_nop 0
	v_pk_mul_f32 v[10:11], v[10:11], v[12:13]
	s_nop 0
	v_cvt_pk_bf16_f32 v9, v10, v11
	v_mul_f32_e32 v10, 0xbfb8aa3b, v4
	v_mul_f32_e32 v11, 0xbfb8aa3b, v5
	v_exp_f32_e32 v10, v10
	v_exp_f32_e32 v11, v11
	v_add_f32_e32 v10, 1.0, v10
	v_add_f32_e32 v11, 1.0, v11
	v_rcp_f32_e32 v10, v10
	v_rcp_f32_e32 v11, v11
	s_nop 0
	v_pk_mul_f32 v[4:5], v[4:5], v[10:11]
	s_nop 0
	v_pk_mul_f32 v[0:1], v[0:1], v[4:5]
	s_nop 0
	v_cvt_pk_bf16_f32 v10, v0, v1
	v_mul_f32_e32 v0, 0xbfb8aa3b, v6
	v_mul_f32_e32 v1, 0xbfb8aa3b, v7
	v_exp_f32_e32 v0, v0
	v_exp_f32_e32 v1, v1
	v_add_f32_e32 v0, 1.0, v0
	v_add_f32_e32 v1, 1.0, v1
	v_rcp_f32_e32 v0, v0
	v_rcp_f32_e32 v1, v1
	s_nop 0
	v_pk_mul_f32 v[0:1], v[6:7], v[0:1]
	s_nop 0
	v_pk_mul_f32 v[0:1], v[2:3], v[0:1]
	s_nop 0
	v_cvt_pk_bf16_f32 v11, v0, v1
	global_store_dwordx4 v[16:17], v[8:11], off sc1
	s_cbranch_vccnz .LBB0_2421
	s_andn2_b64 vcc, exec, s[0:1]
	s_cbranch_vccnz .LBB0_2420
	s_barrier
	s_branch .LBB0_2420

.LBB0_2504:
	v_mbcnt_lo_u32_b32 v130, -1, 0
	v_mbcnt_hi_u32_b32 v130, -1, v130
	s_lshl_b32 s14, s44, 8
	s_lshl_b32 s15, s45, 8
	v_ashrrev_i32_e32 v131, 1, v130
	s_add_i32 s14, s14, s36
	s_or_b32 s15, s15, s37
	v_and_b32_e32 v131, -8, v131
	v_add_u32_e32 v160, s15, v131
	v_and_or_b32 v182, v130, 15, s14
	s_lshr_b32 s14, s44, 4
	v_ashrrev_i32_e32 v161, 31, v160
	v_ashrrev_i32_e32 v183, 31, v182
	s_mulk_i32 s14, 0x1800
	v_lshl_add_u64 v[184:185], v[160:161], 1, s[8:9]
	v_lshlrev_b64 v[130:131], 12, v[182:183]
	s_ashr_i32 s15, s14, 31
	v_lshl_add_u64 v[156:157], v[184:185], 0, v[130:131]
	v_or_b32_e32 v130, 16, v182
	s_lshl_b64 s[14:15], s[14:15], 2
	v_ashrrev_i32_e32 v131, 31, v130
	s_add_u32 s14, s34, s14
	global_load_dwordx4 v[162:165], v[156:157], off
	global_load_dwordx4 v[166:169], v[156:157], off offset:256
	v_lshlrev_b64 v[130:131], 12, v[130:131]
	s_addc_u32 s15, s35, s15
	v_lshl_add_u64 v[174:175], v[184:185], 0, v[130:131]
	v_lshl_add_u64 v[130:131], v[160:161], 2, s[14:15]
	global_load_dwordx4 v[170:173], v[174:175], off
	global_load_dwordx4 v[142:145], v[130:131], off
	global_load_dwordx4 v[138:141], v[130:131], off offset:16
	global_load_dwordx4 v[134:137], v[130:131], off offset:512
	s_nop 0
	global_load_dwordx4 v[130:133], v[130:131], off offset:528
	s_nop 0
	global_load_dwordx4 v[174:177], v[174:175], off offset:256
	v_or_b32_e32 v178, 32, v182
	v_ashrrev_i32_e32 v179, 31, v178
	v_lshlrev_b64 v[178:179], 12, v[178:179]
	v_lshl_add_u64 v[186:187], v[184:185], 0, v[178:179]
	global_load_dwordx4 v[178:181], v[186:187], off
	v_or_b32_e32 v188, 48, v182
	v_ashrrev_i32_e32 v189, 31, v188
	v_lshlrev_b32_e32 v161, 12, v182
	v_lshlrev_b64 v[182:183], 12, v[188:189]
	v_lshl_add_u64 v[190:191], v[184:185], 0, v[182:183]
	global_load_dwordx4 v[182:185], v[186:187], off offset:256
	s_nop 0
	global_load_dwordx4 v[186:189], v[190:191], off
	s_nop 0
	global_load_dwordx4 v[190:193], v[190:191], off offset:256
	v_lshl_add_u32 v160, v160, 1, v161
	v_add_u32_e32 v161, 0x10000, v160
	s_mov_b32 s14, 0x80000
	s_waitcnt vmcnt(0)
	v_lshlrev_b32_e32 v194, 16, v162
	v_and_b32_e32 v195, 0xffff0000, v162
	v_lshlrev_b32_e32 v162, 16, v163
	v_and_b32_e32 v163, 0xffff0000, v163
	v_lshlrev_b32_e32 v196, 16, v164
	v_and_b32_e32 v197, 0xffff0000, v164
	v_lshlrev_b32_e32 v164, 16, v165
	v_and_b32_e32 v165, 0xffff0000, v165
	v_lshlrev_b32_e32 v198, 16, v166
	v_and_b32_e32 v199, 0xffff0000, v166
	v_lshlrev_b32_e32 v166, 16, v167
	v_and_b32_e32 v167, 0xffff0000, v167
	v_lshlrev_b32_e32 v200, 16, v168
	v_and_b32_e32 v201, 0xffff0000, v168
	v_lshlrev_b32_e32 v168, 16, v169
	v_and_b32_e32 v169, 0xffff0000, v169
	v_pk_fma_f32 v[126:127], v[126:127], v[142:143], v[194:195]
	v_pk_fma_f32 v[128:129], v[128:129], v[144:145], v[162:163]
	v_pk_fma_f32 v[122:123], v[122:123], v[138:139], v[196:197]
	v_pk_fma_f32 v[124:125], v[124:125], v[140:141], v[164:165]
	v_pk_fma_f32 v[114:115], v[114:115], v[134:135], v[198:199]
	v_pk_fma_f32 v[116:117], v[116:117], v[136:137], v[166:167]
	v_pk_fma_f32 v[162:163], v[106:107], v[130:131], v[200:201]
	v_pk_fma_f32 v[164:165], v[108:109], v[132:133], v[168:169]
	v_cvt_pk_bf16_f32 v106, v126, v127
	v_cvt_pk_bf16_f32 v107, v128, v129
	v_cvt_pk_bf16_f32 v108, v122, v123
	v_cvt_pk_bf16_f32 v109, v124, v125
	v_lshlrev_b32_e32 v202, 16, v170
	v_and_b32_e32 v203, 0xffff0000, v170
	v_lshlrev_b32_e32 v170, 16, v171
	v_and_b32_e32 v171, 0xffff0000, v171
	v_lshlrev_b32_e32 v204, 16, v172
	v_and_b32_e32 v205, 0xffff0000, v172
	v_cvt_pk_bf16_f32 v114, v114, v115
	v_cvt_pk_bf16_f32 v115, v116, v117
	v_cvt_pk_bf16_f32 v116, v162, v163
	v_cvt_pk_bf16_f32 v117, v164, v165
	buffer_store_dwordx4 v[106:109], v160, s[48:51], 0 offen sc1
	buffer_store_dwordx4 v[114:117], v160, s[48:51], 0 offen offset:256 sc1
	v_pk_fma_f32 v[118:119], v[118:119], v[142:143], v[202:203]
	v_lshlrev_b32_e32 v106, 16, v173
	v_and_b32_e32 v107, 0xffff0000, v173
	v_pk_fma_f32 v[120:121], v[120:121], v[144:145], v[170:171]
	v_pk_fma_f32 v[110:111], v[110:111], v[138:139], v[204:205]
	v_pk_fma_f32 v[112:113], v[112:113], v[140:141], v[106:107]
	v_cvt_pk_bf16_f32 v106, v118, v119
	v_cvt_pk_bf16_f32 v107, v120, v121
	v_cvt_pk_bf16_f32 v108, v110, v111
	v_cvt_pk_bf16_f32 v109, v112, v113
	buffer_store_dwordx4 v[106:109], v161, s[48:51], 0 offen sc1
	s_nop 1
	v_lshlrev_b32_e32 v106, 16, v174
	v_and_b32_e32 v107, 0xffff0000, v174
	v_pk_fma_f32 v[102:103], v[102:103], v[134:135], v[106:107]
	v_lshlrev_b32_e32 v106, 16, v175
	v_and_b32_e32 v107, 0xffff0000, v175
	v_pk_fma_f32 v[104:105], v[104:105], v[136:137], v[106:107]
	v_lshlrev_b32_e32 v106, 16, v176
	v_and_b32_e32 v107, 0xffff0000, v176
	v_pk_fma_f32 v[106:107], v[94:95], v[130:131], v[106:107]
	v_lshlrev_b32_e32 v94, 16, v177
	v_and_b32_e32 v95, 0xffff0000, v177
	v_pk_fma_f32 v[108:109], v[96:97], v[132:133], v[94:95]
	v_cvt_pk_bf16_f32 v94, v102, v103
	v_cvt_pk_bf16_f32 v95, v104, v105
	v_cvt_pk_bf16_f32 v96, v106, v107
	v_cvt_pk_bf16_f32 v97, v108, v109
	buffer_store_dwordx4 v[94:97], v161, s[48:51], 0 offen offset:256 sc1
	v_add_u32_e32 v102, 0x20000, v160
	s_nop 0
	v_lshlrev_b32_e32 v94, 16, v178
	v_and_b32_e32 v95, 0xffff0000, v178
	v_pk_fma_f32 v[94:95], v[98:99], v[142:143], v[94:95]
	v_lshlrev_b32_e32 v98, 16, v180
	v_and_b32_e32 v99, 0xffff0000, v180
	v_lshlrev_b32_e32 v96, 16, v179
	v_and_b32_e32 v97, 0xffff0000, v179
	v_pk_fma_f32 v[98:99], v[90:91], v[138:139], v[98:99]
	v_lshlrev_b32_e32 v90, 16, v181
	v_and_b32_e32 v91, 0xffff0000, v181
	v_pk_fma_f32 v[96:97], v[100:101], v[144:145], v[96:97]
	v_pk_fma_f32 v[100:101], v[92:93], v[140:141], v[90:91]
	v_cvt_pk_bf16_f32 v90, v94, v95
	v_cvt_pk_bf16_f32 v91, v96, v97
	v_cvt_pk_bf16_f32 v92, v98, v99
	v_cvt_pk_bf16_f32 v93, v100, v101
	buffer_store_dwordx4 v[90:93], v102, s[48:51], 0 offen sc1
	v_add_u32_e32 v100, 0x80000, v160
	s_nop 0
	v_lshlrev_b32_e32 v90, 16, v182
	v_and_b32_e32 v91, 0xffff0000, v182
	v_pk_fma_f32 v[86:87], v[86:87], v[134:135], v[90:91]
	v_lshlrev_b32_e32 v90, 16, v183
	v_and_b32_e32 v91, 0xffff0000, v183
	v_pk_fma_f32 v[88:89], v[88:89], v[136:137], v[90:91]
	v_lshlrev_b32_e32 v90, 16, v184
	v_and_b32_e32 v91, 0xffff0000, v184
	v_pk_fma_f32 v[90:91], v[78:79], v[130:131], v[90:91]
	v_lshlrev_b32_e32 v78, 16, v185
	v_and_b32_e32 v79, 0xffff0000, v185
	v_pk_fma_f32 v[92:93], v[80:81], v[132:133], v[78:79]
	v_cvt_pk_bf16_f32 v78, v86, v87
	v_cvt_pk_bf16_f32 v79, v88, v89
	v_cvt_pk_bf16_f32 v80, v90, v91
	v_cvt_pk_bf16_f32 v81, v92, v93
	buffer_store_dwordx4 v[78:81], v102, s[48:51], 0 offen offset:256 sc1
	v_add_u32_e32 v86, 0x30000, v160
	s_nop 0
	v_lshlrev_b32_e32 v78, 16, v186
	v_and_b32_e32 v79, 0xffff0000, v186
	v_pk_fma_f32 v[78:79], v[82:83], v[142:143], v[78:79]
	v_lshlrev_b32_e32 v82, 16, v188
	v_and_b32_e32 v83, 0xffff0000, v188
	v_lshlrev_b32_e32 v80, 16, v187
	v_and_b32_e32 v81, 0xffff0000, v187
	v_pk_fma_f32 v[82:83], v[74:75], v[138:139], v[82:83]
	v_lshlrev_b32_e32 v74, 16, v189
	v_and_b32_e32 v75, 0xffff0000, v189
	v_pk_fma_f32 v[80:81], v[84:85], v[144:145], v[80:81]
	v_pk_fma_f32 v[84:85], v[76:77], v[140:141], v[74:75]
	v_cvt_pk_bf16_f32 v74, v78, v79
	v_cvt_pk_bf16_f32 v75, v80, v81
	v_cvt_pk_bf16_f32 v76, v82, v83
	v_cvt_pk_bf16_f32 v77, v84, v85
	buffer_store_dwordx4 v[74:77], v86, s[48:51], 0 offen sc1
	s_nop 1
	v_lshlrev_b32_e32 v74, 16, v190
	v_and_b32_e32 v75, 0xffff0000, v190
	v_pk_fma_f32 v[70:71], v[70:71], v[134:135], v[74:75]
	v_lshlrev_b32_e32 v74, 16, v191
	v_and_b32_e32 v75, 0xffff0000, v191
	v_pk_fma_f32 v[72:73], v[72:73], v[136:137], v[74:75]
	v_lshlrev_b32_e32 v74, 16, v192
	v_and_b32_e32 v75, 0xffff0000, v192
	v_pk_fma_f32 v[74:75], v[66:67], v[130:131], v[74:75]
	v_lshlrev_b32_e32 v66, 16, v193
	v_and_b32_e32 v67, 0xffff0000, v193
	v_pk_fma_f32 v[76:77], v[68:69], v[132:133], v[66:67]
	v_cvt_pk_bf16_f32 v66, v70, v71
	v_cvt_pk_bf16_f32 v67, v72, v73
	v_cvt_pk_bf16_f32 v68, v74, v75
	v_cvt_pk_bf16_f32 v69, v76, v77
	buffer_store_dwordx4 v[66:69], v86, s[48:51], 0 offen offset:256 sc1
	s_nop 1
	v_add_co_u32_e32 v66, vcc, s14, v156
	s_mov_b64 s[14:15], 0x80000
	s_nop 0
	v_addc_co_u32_e32 v67, vcc, 0, v157, vcc
	global_load_dwordx4 v[70:73], v[66:67], off
	v_lshl_add_u64 v[66:67], v[156:157], 0, s[14:15]
	global_load_dwordx4 v[74:77], v[66:67], off offset:256
	s_mov_b32 s14, 0x90000
	v_add_co_u32_e32 v66, vcc, s14, v156
	s_mov_b64 s[14:15], 0x90000
	s_nop 0
	v_addc_co_u32_e32 v67, vcc, 0, v157, vcc
	global_load_dwordx4 v[78:81], v[66:67], off
	v_lshl_add_u64 v[66:67], v[156:157], 0, s[14:15]
	global_load_dwordx4 v[82:85], v[66:67], off offset:256
	s_mov_b64 s[14:15], 0xa0000
	v_lshl_add_u64 v[66:67], v[156:157], 0, s[14:15]
	s_mov_b32 s14, 0xa0000
	v_add_co_u32_e32 v68, vcc, s14, v156
	s_mov_b64 s[14:15], 0xb0000
	s_nop 0
	v_addc_co_u32_e32 v69, vcc, 0, v157, vcc
	global_load_dwordx4 v[86:89], v[68:69], off
	global_load_dwordx4 v[90:93], v[66:67], off offset:256
	v_lshl_add_u64 v[66:67], v[156:157], 0, s[14:15]
	s_mov_b32 s14, 0xb0000
	v_add_co_u32_e32 v68, vcc, s14, v156
	s_waitcnt vmcnt(5)
	v_lshlrev_b32_e32 v98, 16, v70
	v_addc_co_u32_e32 v69, vcc, 0, v157, vcc
	global_load_dwordx4 v[94:97], v[68:69], off
	s_nop 0
	global_load_dwordx4 v[66:69], v[66:67], off offset:256
	v_and_b32_e32 v99, 0xffff0000, v70
	v_lshlrev_b32_e32 v70, 16, v71
	v_and_b32_e32 v71, 0xffff0000, v71
	v_pk_fma_f32 v[62:63], v[62:63], v[144:145], v[70:71]
	v_lshlrev_b32_e32 v70, 16, v72
	v_and_b32_e32 v71, 0xffff0000, v72
	v_pk_fma_f32 v[70:71], v[56:57], v[138:139], v[70:71]
	v_lshlrev_b32_e32 v56, 16, v73
	v_and_b32_e32 v57, 0xffff0000, v73
	v_pk_fma_f32 v[60:61], v[60:61], v[142:143], v[98:99]
	v_pk_fma_f32 v[72:73], v[58:59], v[140:141], v[56:57]
	v_cvt_pk_bf16_f32 v56, v60, v61
	v_cvt_pk_bf16_f32 v57, v62, v63
	v_cvt_pk_bf16_f32 v58, v70, v71
	v_cvt_pk_bf16_f32 v59, v72, v73
	buffer_store_dwordx4 v[56:59], v100, s[48:51], 0 offen sc1
	s_and_b64 vcc, exec, s[4:5]
	s_mov_b64 s[4:5], -1
	s_waitcnt vmcnt(7)
	v_lshlrev_b32_e32 v56, 16, v74
	v_and_b32_e32 v57, 0xffff0000, v74
	v_pk_fma_f32 v[52:53], v[52:53], v[134:135], v[56:57]
	v_lshlrev_b32_e32 v56, 16, v75
	v_and_b32_e32 v57, 0xffff0000, v75
	v_pk_fma_f32 v[54:55], v[54:55], v[136:137], v[56:57]
	v_lshlrev_b32_e32 v56, 16, v76
	v_and_b32_e32 v57, 0xffff0000, v76
	v_pk_fma_f32 v[56:57], v[44:45], v[130:131], v[56:57]
	v_lshlrev_b32_e32 v44, 16, v77
	v_and_b32_e32 v45, 0xffff0000, v77
	v_pk_fma_f32 v[58:59], v[46:47], v[132:133], v[44:45]
	v_cvt_pk_bf16_f32 v44, v52, v53
	v_cvt_pk_bf16_f32 v45, v54, v55
	v_cvt_pk_bf16_f32 v46, v56, v57
	v_cvt_pk_bf16_f32 v47, v58, v59
	buffer_store_dwordx4 v[44:47], v100, s[48:51], 0 offen offset:256 sc1
	v_add_u32_e32 v52, 0x90000, v160
	s_waitcnt vmcnt(7)
	v_lshlrev_b32_e32 v44, 16, v78
	v_and_b32_e32 v45, 0xffff0000, v78
	v_pk_fma_f32 v[44:45], v[48:49], v[142:143], v[44:45]
	v_lshlrev_b32_e32 v48, 16, v80
	v_and_b32_e32 v49, 0xffff0000, v80
	v_lshlrev_b32_e32 v46, 16, v79
	v_and_b32_e32 v47, 0xffff0000, v79
	v_pk_fma_f32 v[48:49], v[40:41], v[138:139], v[48:49]
	v_lshlrev_b32_e32 v40, 16, v81
	v_and_b32_e32 v41, 0xffff0000, v81
	v_pk_fma_f32 v[46:47], v[50:51], v[144:145], v[46:47]
	v_pk_fma_f32 v[50:51], v[42:43], v[140:141], v[40:41]
	v_cvt_pk_bf16_f32 v40, v44, v45
	v_cvt_pk_bf16_f32 v41, v46, v47
	v_cvt_pk_bf16_f32 v42, v48, v49
	v_cvt_pk_bf16_f32 v43, v50, v51
	buffer_store_dwordx4 v[40:43], v52, s[48:51], 0 offen sc1
	s_waitcnt vmcnt(7)
	s_nop 0
	v_lshlrev_b32_e32 v40, 16, v82
	v_and_b32_e32 v41, 0xffff0000, v82
	v_pk_fma_f32 v[36:37], v[36:37], v[134:135], v[40:41]
	v_lshlrev_b32_e32 v40, 16, v83
	v_and_b32_e32 v41, 0xffff0000, v83
	v_pk_fma_f32 v[38:39], v[38:39], v[136:137], v[40:41]
	v_lshlrev_b32_e32 v40, 16, v84
	v_and_b32_e32 v41, 0xffff0000, v84
	v_pk_fma_f32 v[40:41], v[28:29], v[130:131], v[40:41]
	v_lshlrev_b32_e32 v28, 16, v85
	v_and_b32_e32 v29, 0xffff0000, v85
	v_pk_fma_f32 v[42:43], v[30:31], v[132:133], v[28:29]
	v_cvt_pk_bf16_f32 v28, v36, v37
	v_cvt_pk_bf16_f32 v29, v38, v39
	v_cvt_pk_bf16_f32 v30, v40, v41
	v_cvt_pk_bf16_f32 v31, v42, v43
	buffer_store_dwordx4 v[28:31], v52, s[48:51], 0 offen offset:256 sc1
	v_add_u32_e32 v36, 0xa0000, v160
	s_waitcnt vmcnt(7)
	v_lshlrev_b32_e32 v28, 16, v86
	v_and_b32_e32 v29, 0xffff0000, v86
	v_pk_fma_f32 v[28:29], v[32:33], v[142:143], v[28:29]
	v_lshlrev_b32_e32 v32, 16, v88
	v_and_b32_e32 v33, 0xffff0000, v88
	v_lshlrev_b32_e32 v30, 16, v87
	v_and_b32_e32 v31, 0xffff0000, v87
	v_pk_fma_f32 v[32:33], v[24:25], v[138:139], v[32:33]
	v_lshlrev_b32_e32 v24, 16, v89
	v_and_b32_e32 v25, 0xffff0000, v89
	v_pk_fma_f32 v[30:31], v[34:35], v[144:145], v[30:31]
	v_pk_fma_f32 v[34:35], v[26:27], v[140:141], v[24:25]
	v_cvt_pk_bf16_f32 v24, v28, v29
	v_cvt_pk_bf16_f32 v25, v30, v31
	v_cvt_pk_bf16_f32 v26, v32, v33
	v_cvt_pk_bf16_f32 v27, v34, v35
	buffer_store_dwordx4 v[24:27], v36, s[48:51], 0 offen sc1
	s_waitcnt vmcnt(7)
	s_nop 0
	v_lshlrev_b32_e32 v24, 16, v90
	v_and_b32_e32 v25, 0xffff0000, v90
	v_pk_fma_f32 v[20:21], v[20:21], v[134:135], v[24:25]
	v_lshlrev_b32_e32 v24, 16, v91
	v_and_b32_e32 v25, 0xffff0000, v91
	v_pk_fma_f32 v[22:23], v[22:23], v[136:137], v[24:25]
	v_lshlrev_b32_e32 v24, 16, v92
	v_and_b32_e32 v25, 0xffff0000, v92
	v_pk_fma_f32 v[24:25], v[12:13], v[130:131], v[24:25]
	v_lshlrev_b32_e32 v12, 16, v93
	v_and_b32_e32 v13, 0xffff0000, v93
	v_pk_fma_f32 v[26:27], v[14:15], v[132:133], v[12:13]
	v_cvt_pk_bf16_f32 v12, v20, v21
	v_cvt_pk_bf16_f32 v13, v22, v23
	v_cvt_pk_bf16_f32 v14, v24, v25
	v_cvt_pk_bf16_f32 v15, v26, v27
	buffer_store_dwordx4 v[12:15], v36, s[48:51], 0 offen offset:256 sc1
	v_add_u32_e32 v20, 0xb0000, v160
	s_waitcnt vmcnt(7)
	v_lshlrev_b32_e32 v12, 16, v94
	v_and_b32_e32 v13, 0xffff0000, v94
	v_pk_fma_f32 v[12:13], v[16:17], v[142:143], v[12:13]
	v_lshlrev_b32_e32 v16, 16, v96
	v_and_b32_e32 v17, 0xffff0000, v96
	v_lshlrev_b32_e32 v14, 16, v95
	v_and_b32_e32 v15, 0xffff0000, v95
	v_pk_fma_f32 v[16:17], v[8:9], v[138:139], v[16:17]
	v_lshlrev_b32_e32 v8, 16, v97
	v_and_b32_e32 v9, 0xffff0000, v97
	v_pk_fma_f32 v[14:15], v[18:19], v[144:145], v[14:15]
	v_pk_fma_f32 v[18:19], v[10:11], v[140:141], v[8:9]
	v_cvt_pk_bf16_f32 v8, v12, v13
	v_cvt_pk_bf16_f32 v9, v14, v15
	v_cvt_pk_bf16_f32 v10, v16, v17
	v_cvt_pk_bf16_f32 v11, v18, v19
	buffer_store_dwordx4 v[8:11], v20, s[48:51], 0 offen sc1
	s_waitcnt vmcnt(7)
	s_nop 0
	v_lshlrev_b32_e32 v8, 16, v66
	v_and_b32_e32 v9, 0xffff0000, v66
	v_pk_fma_f32 v[4:5], v[4:5], v[134:135], v[8:9]
	v_lshlrev_b32_e32 v8, 16, v67
	v_and_b32_e32 v9, 0xffff0000, v67
	v_pk_fma_f32 v[6:7], v[6:7], v[136:137], v[8:9]
	v_lshlrev_b32_e32 v8, 16, v68
	v_and_b32_e32 v9, 0xffff0000, v68
	v_pk_fma_f32 v[8:9], v[0:1], v[130:131], v[8:9]
	v_lshlrev_b32_e32 v0, 16, v69
	v_and_b32_e32 v1, 0xffff0000, v69
	v_pk_fma_f32 v[10:11], v[2:3], v[132:133], v[0:1]
	v_cvt_pk_bf16_f32 v0, v4, v5
	v_cvt_pk_bf16_f32 v1, v6, v7
	v_cvt_pk_bf16_f32 v2, v8, v9
	v_cvt_pk_bf16_f32 v3, v10, v11
	buffer_store_dwordx4 v[0:3], v20, s[48:51], 0 offen offset:256 sc1
	s_cbranch_vccnz .LBB0_2489
	s_andn2_b64 vcc, exec, s[0:1]
	s_cbranch_vccnz .LBB0_2488
	s_barrier
	s_branch .LBB0_2488
